# grid barrier: each workgroup issues its L1 invalidate before polling (only sc1 polls and atomics between arrival and release) instead of after the release
# speedup vs baseline: 1.0629x; 1.0152x over previous
.LBB0_157:
	s_lshl_b32 s6, s1, 8
	s_add_u32 s6, s96, s6
	s_addc_u32 s7, s97, 0
	v_mov_b32_e32 v2, 0x1000
	v_mov_b32_e32 v4, 1
	global_atomic_add v4, v2, v4, s[6:7] offset:1024 sc0
	v_cvt_f32_u32_e32 v2, v3
	v_sub_u32_e32 v5, 0, v3
	v_rcp_iflag_f32_e32 v2, v2
	s_nop 0
	v_mul_f32_e32 v2, 0x4f7ffffe, v2
	v_cvt_u32_f32_e32 v2, v2
	v_mul_lo_u32 v5, v5, v2
	v_mul_hi_u32 v5, v2, v5
	v_add_u32_e32 v2, v2, v5
	s_waitcnt vmcnt(0)
	v_mul_hi_u32 v2, v4, v2
	v_mul_lo_u32 v5, v2, v3
	v_sub_u32_e32 v5, v4, v5
	v_add_u32_e32 v6, 1, v2
	v_cmp_ge_u32_e32 vcc, v5, v3
	v_add_u32_e32 v4, 1, v4
	s_nop 0
	v_cndmask_b32_e32 v2, v2, v6, vcc
	v_sub_u32_e32 v6, v5, v3
	v_cndmask_b32_e32 v5, v5, v6, vcc
	v_add_u32_e32 v6, 1, v2
	v_cmp_ge_u32_e32 vcc, v5, v3
	s_nop 1
	v_cndmask_b32_e32 v2, v2, v6, vcc
	v_mul_lo_u32 v5, v3, v2
	v_add_u32_e32 v3, v5, v3
	v_cmp_ne_u32_e32 vcc, v4, v3
	s_and_saveexec_b64 s[8:9], vcc
	s_xor_b64 s[8:9], exec, s[8:9]
	s_cbranch_execz .LBB0_171
	s_waitcnt lgkmcnt(0)
	v_mov_b32_e32 v1, 0x2000
	buffer_inv sc1
	global_load_dword v1, v1, s[6:7] offset:1024 sc1
	s_add_u32 s14, s6, 0x2400
	s_addc_u32 s15, s7, 0
	s_waitcnt vmcnt(0)
	v_cmp_eq_u32_e32 vcc, v1, v2
	s_and_saveexec_b64 s[10:11], vcc
	s_cbranch_execz .LBB0_170
	s_add_u32 s12, s24, 0x4200
	s_addc_u32 s13, s25, 0
	s_mov_b32 s21, 1
	s_mov_b64 s[16:17], 0
	v_mov_b32_e32 v1, 0
	s_branch .LBB0_161

.LBB0_170:
	s_or_b64 exec, exec, s[10:11]
	s_waitcnt vmcnt(0)
	s_waitcnt vmcnt(0)
.LBB0_171:
	s_andn2_saveexec_b64 s[8:9], s[8:9]
	s_cbranch_execz .LBB0_189
	s_mov_b64 s[8:9], exec
	buffer_wbl2 sc1
	s_waitcnt lgkmcnt(0)
	s_waitcnt vmcnt(0)
	buffer_inv sc1
	v_mbcnt_lo_u32_b32 v2, s8, 0
	v_mbcnt_hi_u32_b32 v2, s9, v2
	v_cmp_eq_u32_e32 vcc, 0, v2
	s_and_saveexec_b64 s[10:11], vcc
	s_cbranch_execz .LBB0_174
	s_bcnt1_i32_b64 s8, s[8:9]
	v_mov_b32_e32 v3, 0x7000
	v_mov_b32_e32 v4, s8
	global_atomic_add v3, v3, v4, s[24:25] offset:1024 sc0

.LBB0_188:
	s_or_b64 exec, exec, s[8:9]
	v_mov_b32_e32 v1, 0x2000
	v_mov_b32_e32 v2, 1
	s_waitcnt vmcnt(0)
	global_atomic_add v1, v2, s[6:7] offset:1024
	s_waitcnt vmcnt(0)

.LBB0_1254:
	s_lshl_b32 s4, s1, 8
	s_add_u32 s4, s96, s4
	s_addc_u32 s5, s97, 0
	v_mov_b32_e32 v2, 0x1000
	v_mov_b32_e32 v4, 1
	global_atomic_add v4, v2, v4, s[4:5] offset:1024 sc0
	v_cvt_f32_u32_e32 v2, v3
	v_sub_u32_e32 v5, 0, v3
	v_rcp_iflag_f32_e32 v2, v2
	s_nop 0
	v_mul_f32_e32 v2, 0x4f7ffffe, v2
	v_cvt_u32_f32_e32 v2, v2
	v_mul_lo_u32 v5, v5, v2
	v_mul_hi_u32 v5, v2, v5
	v_add_u32_e32 v2, v2, v5
	s_waitcnt vmcnt(0)
	v_mul_hi_u32 v2, v4, v2
	v_mul_lo_u32 v5, v2, v3
	v_sub_u32_e32 v5, v4, v5
	v_add_u32_e32 v6, 1, v2
	v_cmp_ge_u32_e32 vcc, v5, v3
	v_add_u32_e32 v4, 1, v4
	s_nop 0
	v_cndmask_b32_e32 v2, v2, v6, vcc
	v_sub_u32_e32 v6, v5, v3
	v_cndmask_b32_e32 v5, v5, v6, vcc
	v_add_u32_e32 v6, 1, v2
	v_cmp_ge_u32_e32 vcc, v5, v3
	s_nop 1
	v_cndmask_b32_e32 v2, v2, v6, vcc
	v_mul_lo_u32 v5, v3, v2
	v_add_u32_e32 v3, v5, v3
	v_cmp_ne_u32_e32 vcc, v4, v3
	s_and_saveexec_b64 s[6:7], vcc
	s_xor_b64 s[6:7], exec, s[6:7]
	s_cbranch_execz .LBB0_1268
	s_waitcnt lgkmcnt(0)
	v_mov_b32_e32 v1, 0x2000
	buffer_inv sc1
	global_load_dword v1, v1, s[4:5] offset:1024 sc1
	s_add_u32 s12, s4, 0x2400
	s_addc_u32 s13, s5, 0
	s_waitcnt vmcnt(0)
	v_cmp_eq_u32_e32 vcc, v1, v2
	s_and_saveexec_b64 s[8:9], vcc
	s_cbranch_execz .LBB0_1267
	s_add_u32 s10, s24, 0x4200
	s_addc_u32 s11, s25, 0
	s_mov_b32 s21, 1
	s_mov_b64 s[14:15], 0
	v_mov_b32_e32 v1, 0
	s_branch .LBB0_1258

.LBB0_1267:
	s_or_b64 exec, exec, s[8:9]
	s_waitcnt vmcnt(0)
	s_waitcnt vmcnt(0)
.LBB0_1268:
	s_andn2_saveexec_b64 s[6:7], s[6:7]
	s_cbranch_execz .LBB0_1286
	s_mov_b64 s[6:7], exec
	buffer_wbl2 sc1
	s_waitcnt lgkmcnt(0)
	s_waitcnt vmcnt(0)
	buffer_inv sc1
	v_mbcnt_lo_u32_b32 v2, s6, 0
	v_mbcnt_hi_u32_b32 v2, s7, v2
	v_cmp_eq_u32_e32 vcc, 0, v2
	s_and_saveexec_b64 s[8:9], vcc
	s_cbranch_execz .LBB0_1271
	s_bcnt1_i32_b64 s6, s[6:7]
	v_mov_b32_e32 v3, 0x7000
	v_mov_b32_e32 v4, s6
	global_atomic_add v3, v3, v4, s[24:25] offset:1024 sc0

.LBB0_1285:
	s_or_b64 exec, exec, s[6:7]
	v_mov_b32_e32 v1, 0x2000
	v_mov_b32_e32 v2, 1
	s_waitcnt vmcnt(0)
	global_atomic_add v1, v2, s[4:5] offset:1024
	s_waitcnt vmcnt(0)

.LBB0_2145:
	s_lshl_b32 s1, s1, 8
	s_add_u32 s4, s96, s1
	s_addc_u32 s5, s97, 0
	v_mov_b32_e32 v2, 0x1000
	v_mov_b32_e32 v4, 1
	global_atomic_add v4, v2, v4, s[4:5] offset:1024 sc0
	v_cvt_f32_u32_e32 v2, v3
	v_sub_u32_e32 v5, 0, v3
	v_rcp_iflag_f32_e32 v2, v2
	s_nop 0
	v_mul_f32_e32 v2, 0x4f7ffffe, v2
	v_cvt_u32_f32_e32 v2, v2
	v_mul_lo_u32 v5, v5, v2
	v_mul_hi_u32 v5, v2, v5
	v_add_u32_e32 v2, v2, v5
	s_waitcnt vmcnt(0)
	v_mul_hi_u32 v2, v4, v2
	v_mul_lo_u32 v5, v2, v3
	v_sub_u32_e32 v5, v4, v5
	v_add_u32_e32 v6, 1, v2
	v_cmp_ge_u32_e32 vcc, v5, v3
	v_add_u32_e32 v4, 1, v4
	s_nop 0
	v_cndmask_b32_e32 v2, v2, v6, vcc
	v_sub_u32_e32 v6, v5, v3
	v_cndmask_b32_e32 v5, v5, v6, vcc
	v_add_u32_e32 v6, 1, v2
	v_cmp_ge_u32_e32 vcc, v5, v3
	s_nop 1
	v_cndmask_b32_e32 v2, v2, v6, vcc
	v_mul_lo_u32 v5, v3, v2
	v_add_u32_e32 v3, v5, v3
	v_cmp_ne_u32_e32 vcc, v4, v3
	s_and_saveexec_b64 s[6:7], vcc
	s_xor_b64 s[6:7], exec, s[6:7]
	s_cbranch_execz .LBB0_2159
	s_waitcnt lgkmcnt(0)
	v_mov_b32_e32 v1, 0x2000
	buffer_inv sc1
	global_load_dword v1, v1, s[4:5] offset:1024 sc1
	s_add_u32 s12, s4, 0x2400
	s_addc_u32 s13, s5, 0
	s_waitcnt vmcnt(0)
	v_cmp_eq_u32_e32 vcc, v1, v2
	s_and_saveexec_b64 s[8:9], vcc
	s_cbranch_execz .LBB0_2158
	s_add_u32 s10, s24, 0x4200
	s_addc_u32 s11, s25, 0
	s_mov_b32 s1, 1
	s_mov_b64 s[14:15], 0
	v_mov_b32_e32 v1, 0
	s_branch .LBB0_2149

.LBB0_2159:
	s_andn2_saveexec_b64 s[6:7], s[6:7]
	s_cbranch_execz .LBB0_2177
	s_mov_b64 s[6:7], exec
	buffer_wbl2 sc1
	s_waitcnt lgkmcnt(0)
	s_waitcnt vmcnt(0)
	buffer_inv sc1
	v_mbcnt_lo_u32_b32 v2, s6, 0
	v_mbcnt_hi_u32_b32 v2, s7, v2
	v_cmp_eq_u32_e32 vcc, 0, v2
	s_and_saveexec_b64 s[8:9], vcc
	s_cbranch_execz .LBB0_2162
	s_bcnt1_i32_b64 s1, s[6:7]
	v_mov_b32_e32 v3, 0x7000
	v_mov_b32_e32 v4, s1
	global_atomic_add v3, v3, v4, s[24:25] offset:1024 sc0
